# plus NORM fix-path: 16 partial-slab loads per wait; GEMM tile prologue: dead duplicate accumulator zeroing removed, rest hoisted above first-tile wait
# speedup vs baseline: 1.0835x; 1.0036x over previous
.LBB0_623:
	s_and_b64 vcc, exec, s[10:11]
	s_cbranch_vccz .LBB0_628
	v_readlane_b32 s2, v254, 3
	v_readlane_b32 s3, v255, 39
	s_add_i32 s8, s3, s2
	s_mul_i32 s34, s8, 0xb00
	s_lshl_b64 s[2:3], s[34:35], 1
	v_readlane_b32 s4, v255, 30
	v_readlane_b32 s5, v255, 31
	s_add_u32 s2, s4, s2
	s_addc_u32 s3, s5, s3
	v_readlane_b32 s5, v254, 4
	v_mov_b32_e32 v170, v163
	s_mul_i32 s4, s5, 0x1600
	v_readlane_b32 s6, v255, 32
	v_readlane_b32 s7, v255, 33
	v_ashrrev_i32_e32 v0, 6, v170
	s_waitcnt vmcnt(3)
	v_and_b32_e32 v2, 63, v170
	s_add_u32 s4, s6, s4
	s_mul_hi_i32 s5, s5, 0x1600
	s_waitcnt vmcnt(2)
	v_bfe_u32 v7, v170, 3, 3
	v_bfe_u32 v171, v170, 4, 2
	s_addc_u32 s5, s7, s5
	v_readlane_b32 s9, v255, 9
	v_lshlrev_b32_e32 v173, 4, v2
	v_lshl_or_b32 v2, v0, 5, v7
	v_xor_b32_e32 v4, v171, v170
	s_movk_i32 s24, 0xb00
	s_add_u32 s6, s2, s9
	v_mad_i64_i32 v[2:3], s[14:15], v2, s24, 0
	v_lshlrev_b32_e32 v4, 3, v4
	v_lshlrev_b32_e32 v174, 12, v0
	s_addc_u32 s7, s3, 0
	v_lshlrev_b64 v[164:165], 1, v[2:3]
	v_and_b32_e32 v4, 56, v4
	v_or_b32_e32 v8, v173, v174
	v_lshlrev_b32_e32 v6, 2, v0
	s_add_u32 s10, s4, s9
	v_lshl_add_u64 v[2:3], s[6:7], 0, v[164:165]
	s_waitcnt vmcnt(0)
	v_lshlrev_b32_e32 v130, 1, v4
	v_mov_b32_e32 v131, v1
	v_readfirstlane_b32 s9, v8
	v_add_u32_e32 v0, 0x8000, v8
	s_addc_u32 s11, s5, 0
	v_lshl_add_u64 v[2:3], v[2:3], 0, v[130:131]
	s_mov_b32 m0, s9
	v_readfirstlane_b32 s9, v0
	v_or_b32_e32 v0, 1, v6
	v_lshl_add_u64 v[4:5], s[10:11], 0, v[164:165]
	global_load_lds_dwordx4 v[2:3], off
	v_lshl_or_b32 v2, v0, 3, v7
	v_lshl_add_u64 v[4:5], v[4:5], 0, v[130:131]
	s_mov_b32 m0, s9
	v_lshrrev_b32_e32 v3, 1, v2
	global_load_lds_dwordx4 v[4:5], off
	v_xor_b32_e32 v4, v3, v170
	v_mad_i64_i32 v[2:3], s[14:15], v2, s24, 0
	v_lshlrev_b32_e32 v4, 3, v4
	v_lshlrev_b32_e32 v175, 10, v0
	v_lshlrev_b64 v[168:169], 1, v[2:3]
	v_and_b32_e32 v4, 56, v4
	v_or_b32_e32 v9, v173, v175
	v_lshl_add_u64 v[2:3], s[6:7], 0, v[168:169]
	v_lshlrev_b32_e32 v132, 1, v4
	v_mov_b32_e32 v133, v1
	v_readfirstlane_b32 s9, v9
	v_add_u32_e32 v0, 0x8000, v9
	v_or_b32_e32 v10, 2, v6
	v_lshl_add_u64 v[2:3], v[2:3], 0, v[132:133]
	v_lshl_add_u64 v[4:5], s[10:11], 0, v[168:169]
	s_mov_b32 m0, s9
	v_readfirstlane_b32 s9, v0
	v_lshl_or_b32 v0, v10, 3, v7
	v_lshl_add_u64 v[4:5], v[4:5], 0, v[132:133]
	global_load_lds_dwordx4 v[2:3], off
	s_mov_b32 m0, s9
	v_lshrrev_b32_e32 v2, 1, v0
	global_load_lds_dwordx4 v[4:5], off
	v_xor_b32_e32 v4, v2, v170
	v_mad_i64_i32 v[2:3], s[14:15], v0, s24, 0
	v_lshlrev_b32_e32 v0, 3, v4
	v_lshlrev_b32_e32 v176, 10, v10
	v_lshlrev_b64 v[154:155], 1, v[2:3]
	v_and_b32_e32 v0, 56, v0
	v_or_b32_e32 v10, v173, v176
	v_lshl_add_u64 v[2:3], s[6:7], 0, v[154:155]
	v_lshlrev_b32_e32 v0, 1, v0
	v_readfirstlane_b32 s9, v10
	v_lshl_add_u64 v[2:3], v[2:3], 0, v[0:1]
	s_mov_b32 m0, s9
	v_or_b32_e32 v6, 3, v6
	global_load_lds_dwordx4 v[2:3], off
	v_add_u32_e32 v2, 0x8000, v10
	v_lshl_add_u64 v[4:5], s[10:11], 0, v[154:155]
	v_readfirstlane_b32 s9, v2
	v_lshl_or_b32 v2, v6, 3, v7
	v_lshl_add_u64 v[4:5], v[4:5], 0, v[0:1]
	s_mov_b32 m0, s9
	v_lshrrev_b32_e32 v3, 1, v2
	global_load_lds_dwordx4 v[4:5], off
	v_xor_b32_e32 v4, v3, v170
	v_mad_i64_i32 v[2:3], s[14:15], v2, s24, 0
	v_lshlrev_b32_e32 v4, 3, v4
	v_lshlrev_b32_e32 v177, 10, v6
	v_lshlrev_b64 v[156:157], 1, v[2:3]
	v_and_b32_e32 v4, 56, v4
	v_or_b32_e32 v6, v173, v177
	v_lshl_add_u64 v[2:3], s[6:7], 0, v[156:157]
	v_lshlrev_b32_e32 v158, 1, v4
	v_mov_b32_e32 v159, v1
	v_readfirstlane_b32 s6, v6
	v_lshl_add_u64 v[2:3], v[2:3], 0, v[158:159]
	v_lshl_add_u64 v[4:5], s[10:11], 0, v[156:157]
	s_mov_b32 m0, s6
	v_readlane_b32 s10, v255, 10
	global_load_lds_dwordx4 v[2:3], off
	v_add_u32_e32 v2, 0x8000, v6
	v_readlane_b32 s11, v255, 11
	v_readfirstlane_b32 s6, v2
	v_lshl_add_u64 v[2:3], s[2:3], 0, v[164:165]
	s_mov_b32 s11, s35
	v_add_u32_e32 v6, 0x10000, v8
	v_lshl_add_u64 v[4:5], v[4:5], 0, v[158:159]
	s_mov_b32 m0, s6
	v_lshl_add_u64 v[2:3], v[2:3], 0, s[10:11]
	v_readfirstlane_b32 s6, v6
	global_load_lds_dwordx4 v[4:5], off
	v_lshl_add_u64 v[2:3], v[2:3], 0, v[130:131]
	s_mov_b32 m0, s6
	v_mov_b32_e32 v123, 0
	v_mov_b32_e32 v124, 0
	v_mov_b32_e32 v125, 0
	v_mov_b32_e32 v126, 0
	v_mov_b32_e32 v127, 0
	v_mov_b32_e32 v128, 0
	v_mov_b32_e32 v129, 0
	v_mov_b32_e32 v118, 0
	v_mov_b32_e32 v119, 0
	v_mov_b32_e32 v120, 0
	v_mov_b32_e32 v121, 0
	v_mov_b32_e32 v114, 0
	v_mov_b32_e32 v115, 0
	v_mov_b32_e32 v116, 0
	v_mov_b32_e32 v117, 0
	v_mov_b32_e32 v110, 0
	v_mov_b32_e32 v111, 0
	v_mov_b32_e32 v112, 0
	v_mov_b32_e32 v113, 0
	v_mov_b32_e32 v106, 0
	v_mov_b32_e32 v107, 0
	v_mov_b32_e32 v108, 0
	v_mov_b32_e32 v109, 0
	v_mov_b32_e32 v102, 0
	v_mov_b32_e32 v103, 0
	v_mov_b32_e32 v104, 0
	v_mov_b32_e32 v105, 0
	v_mov_b32_e32 v98, 0
	v_mov_b32_e32 v99, 0
	v_mov_b32_e32 v100, 0
	v_mov_b32_e32 v101, 0
	v_mov_b32_e32 v94, 0
	v_mov_b32_e32 v95, 0
	v_mov_b32_e32 v96, 0
	v_mov_b32_e32 v97, 0
	v_mov_b32_e32 v90, 0
	v_mov_b32_e32 v91, 0
	v_mov_b32_e32 v92, 0
	v_mov_b32_e32 v93, 0
	v_mov_b32_e32 v86, 0
	v_mov_b32_e32 v87, 0
	v_mov_b32_e32 v88, 0
	v_mov_b32_e32 v89, 0
	v_mov_b32_e32 v82, 0
	v_mov_b32_e32 v83, 0
	v_mov_b32_e32 v84, 0
	v_mov_b32_e32 v85, 0
	v_mov_b32_e32 v78, 0
	v_mov_b32_e32 v79, 0
	v_mov_b32_e32 v80, 0
	v_mov_b32_e32 v81, 0
	v_mov_b32_e32 v74, 0
	v_mov_b32_e32 v75, 0
	v_mov_b32_e32 v76, 0
	v_mov_b32_e32 v77, 0
	v_mov_b32_e32 v70, 0
	v_mov_b32_e32 v71, 0
	v_mov_b32_e32 v72, 0
	v_mov_b32_e32 v73, 0
	v_mov_b32_e32 v66, 0
	v_mov_b32_e32 v67, 0
	v_mov_b32_e32 v68, 0
	v_mov_b32_e32 v69, 0
	v_mov_b32_e32 v62, 0
	v_mov_b32_e32 v63, 0
	v_mov_b32_e32 v64, 0
	v_mov_b32_e32 v65, 0
	v_mov_b32_e32 v58, 0
	v_mov_b32_e32 v59, 0
	v_mov_b32_e32 v60, 0
	v_mov_b32_e32 v61, 0
	v_mov_b32_e32 v54, 0
	v_mov_b32_e32 v55, 0
	v_mov_b32_e32 v56, 0
	v_mov_b32_e32 v57, 0
	v_mov_b32_e32 v50, 0
	v_mov_b32_e32 v51, 0
	v_mov_b32_e32 v52, 0
	v_mov_b32_e32 v53, 0
	v_mov_b32_e32 v46, 0
	v_mov_b32_e32 v47, 0
	v_mov_b32_e32 v48, 0
	v_mov_b32_e32 v49, 0
	v_mov_b32_e32 v38, 0
	v_mov_b32_e32 v39, 0
	v_mov_b32_e32 v40, 0
	v_mov_b32_e32 v41, 0
	v_mov_b32_e32 v26, 0
	v_mov_b32_e32 v27, 0
	v_mov_b32_e32 v28, 0
	v_mov_b32_e32 v29, 0
	v_mov_b32_e32 v18, 0
	v_mov_b32_e32 v19, 0
	v_mov_b32_e32 v20, 0
	v_mov_b32_e32 v21, 0
	v_mov_b32_e32 v42, 0
	v_mov_b32_e32 v43, 0
	v_mov_b32_e32 v44, 0
	v_mov_b32_e32 v45, 0
	v_mov_b32_e32 v34, 0
	v_mov_b32_e32 v35, 0
	v_mov_b32_e32 v36, 0
	v_mov_b32_e32 v37, 0
	v_mov_b32_e32 v30, 0
	v_mov_b32_e32 v31, 0
	v_mov_b32_e32 v32, 0
	v_mov_b32_e32 v33, 0
	v_mov_b32_e32 v22, 0
	v_mov_b32_e32 v23, 0
	v_mov_b32_e32 v24, 0
	v_mov_b32_e32 v25, 0
	v_mov_b32_e32 v14, 0
	v_mov_b32_e32 v15, 0
	v_mov_b32_e32 v16, 0
	v_mov_b32_e32 v17, 0
	v_mov_b32_e32 v12, 0
	v_mov_b32_e32 v13, 0
	s_waitcnt vmcnt(0)
	s_waitcnt vmcnt(0) lgkmcnt(0)
	s_barrier
	global_load_lds_dwordx4 v[2:3], off
	v_add_u32_e32 v2, 0x18000, v8
	v_lshl_add_u64 v[4:5], s[4:5], 0, v[164:165]
	v_readfirstlane_b32 s6, v2
	s_mov_b32 m0, s6
	s_mov_b32 s6, s10
	v_lshl_add_u64 v[4:5], v[4:5], 0, s[10:11]
	v_lshl_add_u64 v[2:3], s[2:3], 0, v[168:169]
	v_writelane_b32 v255, s6, 10
	v_add_u32_e32 v6, 0x10000, v9
	v_lshl_add_u64 v[4:5], v[4:5], 0, v[130:131]
	v_lshl_add_u64 v[2:3], v[2:3], 0, s[10:11]
	v_writelane_b32 v255, s7, 11
	v_readfirstlane_b32 s6, v6
	global_load_lds_dwordx4 v[4:5], off
	v_lshl_add_u64 v[2:3], v[2:3], 0, v[132:133]
	s_mov_b32 m0, s6
	v_lshl_add_u64 v[4:5], s[4:5], 0, v[168:169]
	global_load_lds_dwordx4 v[2:3], off
	v_add_u32_e32 v2, 0x18000, v9
	v_lshl_add_u64 v[4:5], v[4:5], 0, s[10:11]
	v_readfirstlane_b32 s6, v2
	v_lshl_add_u64 v[4:5], v[4:5], 0, v[132:133]
	s_mov_b32 m0, s6
	v_and_b32_e32 v134, 15, v170
	global_load_lds_dwordx4 v[4:5], off
	v_ashrrev_i32_e32 v2, 1, v170
	s_movk_i32 s6, 0xff80
	v_and_or_b32 v172, v2, s6, v134
	v_readlane_b32 s6, v254, 6
	v_mov_b32_e32 v5, 0
	v_readlane_b32 s7, v254, 7
	s_andn2_b64 vcc, exec, s[6:7]
	s_cbranch_vccnz .Lgemm_skip_zero_b
	v_lshrrev_b32_e32 v10, 1, v134
	v_lshlrev_b32_e32 v2, 7, v170
	v_and_b32_e32 v179, 0x6780, v2
	v_xor_b32_e32 v2, v171, v10
	v_lshlrev_b32_e32 v178, 7, v172
	v_lshlrev_b32_e32 v180, 4, v2
	v_or_b32_e32 v11, v178, v180
	ds_read_b128 v[146:149], v11 offset:2048
	ds_read_b128 v[150:153], v11
	v_or_b32_e32 v11, v179, v180
	v_lshl_add_u64 v[2:3], s[4:5], 0, v[132:133]
	v_lshl_add_u64 v[4:5], s[2:3], 0, v[132:133]
	v_lshl_add_u64 v[6:7], s[4:5], 0, v[130:131]
	v_lshl_add_u64 v[8:9], s[2:3], 0, v[130:131]
	ds_read_b128 v[130:133], v11 offset:38912
	ds_read_b128 v[134:137], v11 offset:36864
	ds_read_b128 v[138:141], v11 offset:34816
	ds_read_b128 v[142:145], v11 offset:32768
	v_bitop3_b32 v10, v171, v10, 4 bitop3:0x36
	v_mov_b32_e32 v122, 0
	v_lshlrev_b32_e32 v181, 4, v10
	v_lshl_add_u64 v[160:161], v[8:9], 0, v[164:165]
	v_lshl_add_u64 v[164:165], v[6:7], 0, v[164:165]
	v_lshl_add_u64 v[166:167], v[4:5], 0, v[168:169]
	v_lshl_add_u64 v[168:169], v[2:3], 0, v[168:169]
	s_mov_b32 s9, 0
	v_readlane_b32 s6, v254, 5
	v_mov_b32_e32 v10, v122
	v_mov_b32_e32 v11, v122
	v_mov_b32_e32 v6, v122
	v_mov_b32_e32 v7, v122
	v_mov_b32_e32 v8, v122
	v_mov_b32_e32 v9, v122
	v_mov_b32_e32 v2, v122
	v_mov_b32_e32 v3, v122
	v_mov_b32_e32 v4, v122
	v_mov_b32_e32 v5, v122
	v_readlane_b32 s31, v254, 8
	v_readlane_b32 s38, v254, 9

.Lgemm_skip_zero_a:
	v_mov_b32_e32 v5, 0
	v_mov_b32_e32 v4, v5
	v_mov_b32_e32 v3, v5
	v_mov_b32_e32 v2, v5
	v_mov_b32_e32 v9, v5
	v_mov_b32_e32 v8, v5
	v_mov_b32_e32 v7, v5
	v_mov_b32_e32 v6, v5
	v_mov_b32_e32 v13, v5
	v_mov_b32_e32 v12, v5
	v_mov_b32_e32 v11, v5
	v_mov_b32_e32 v10, v5
	v_mov_b32_e32 v17, v5
	v_mov_b32_e32 v16, v5
	v_mov_b32_e32 v15, v5
	v_mov_b32_e32 v14, v5
	v_mov_b32_e32 v21, v5
	v_mov_b32_e32 v20, v5
	v_mov_b32_e32 v19, v5
	v_mov_b32_e32 v18, v5
	v_mov_b32_e32 v25, v5
	v_mov_b32_e32 v24, v5
	v_mov_b32_e32 v23, v5
	v_mov_b32_e32 v22, v5
	v_mov_b32_e32 v29, v5
	v_mov_b32_e32 v28, v5
	v_mov_b32_e32 v27, v5
	v_mov_b32_e32 v26, v5
	v_mov_b32_e32 v41, v5
	v_mov_b32_e32 v40, v5
	v_mov_b32_e32 v39, v5
	v_mov_b32_e32 v38, v5
	v_mov_b32_e32 v33, v5
	v_mov_b32_e32 v32, v5
	v_mov_b32_e32 v31, v5
	v_mov_b32_e32 v30, v5
	v_mov_b32_e32 v37, v5
	v_mov_b32_e32 v36, v5
	v_mov_b32_e32 v35, v5
	v_mov_b32_e32 v34, v5
	v_mov_b32_e32 v45, v5
	v_mov_b32_e32 v44, v5
	v_mov_b32_e32 v43, v5
	v_mov_b32_e32 v42, v5
	v_mov_b32_e32 v49, v5
	v_mov_b32_e32 v48, v5
	v_mov_b32_e32 v47, v5
	v_mov_b32_e32 v46, v5
	v_mov_b32_e32 v53, v5
	v_mov_b32_e32 v52, v5
	v_mov_b32_e32 v51, v5
	v_mov_b32_e32 v50, v5
	v_mov_b32_e32 v57, v5
	v_mov_b32_e32 v56, v5
	v_mov_b32_e32 v55, v5
	v_mov_b32_e32 v54, v5
	v_mov_b32_e32 v61, v5
	v_mov_b32_e32 v60, v5
	v_mov_b32_e32 v59, v5
	v_mov_b32_e32 v58, v5
	v_mov_b32_e32 v65, v5
	v_mov_b32_e32 v64, v5
	v_mov_b32_e32 v63, v5
	v_mov_b32_e32 v62, v5
	v_mov_b32_e32 v69, v5
	v_mov_b32_e32 v68, v5
	v_mov_b32_e32 v67, v5
	v_mov_b32_e32 v66, v5
	v_mov_b32_e32 v73, v5
	v_mov_b32_e32 v72, v5
	v_mov_b32_e32 v71, v5
	v_mov_b32_e32 v70, v5
	v_mov_b32_e32 v77, v5
	v_mov_b32_e32 v76, v5
	v_mov_b32_e32 v75, v5
	v_mov_b32_e32 v74, v5
	v_mov_b32_e32 v81, v5
	v_mov_b32_e32 v80, v5
	v_mov_b32_e32 v79, v5
	v_mov_b32_e32 v78, v5
	v_mov_b32_e32 v85, v5
	v_mov_b32_e32 v84, v5
	v_mov_b32_e32 v83, v5
	v_mov_b32_e32 v82, v5
	v_mov_b32_e32 v89, v5
	v_mov_b32_e32 v88, v5
	v_mov_b32_e32 v87, v5
	v_mov_b32_e32 v86, v5
	v_mov_b32_e32 v93, v5
	v_mov_b32_e32 v92, v5
	v_mov_b32_e32 v91, v5
	v_mov_b32_e32 v90, v5
	v_mov_b32_e32 v97, v5
	v_mov_b32_e32 v96, v5
	v_mov_b32_e32 v95, v5
	v_mov_b32_e32 v94, v5
	v_mov_b32_e32 v101, v5
	v_mov_b32_e32 v100, v5
	v_mov_b32_e32 v99, v5
	v_mov_b32_e32 v98, v5
	v_mov_b32_e32 v105, v5
	v_mov_b32_e32 v104, v5
	v_mov_b32_e32 v103, v5
	v_mov_b32_e32 v102, v5
	v_mov_b32_e32 v109, v5
	v_mov_b32_e32 v108, v5
	v_mov_b32_e32 v107, v5
	v_mov_b32_e32 v106, v5
	v_mov_b32_e32 v113, v5
	v_mov_b32_e32 v112, v5
	v_mov_b32_e32 v111, v5
	v_mov_b32_e32 v110, v5
	v_mov_b32_e32 v117, v5
	v_mov_b32_e32 v116, v5
	v_mov_b32_e32 v115, v5
	v_mov_b32_e32 v114, v5
	v_mov_b32_e32 v121, v5
	v_mov_b32_e32 v120, v5
	v_mov_b32_e32 v119, v5
	v_mov_b32_e32 v118, v5
	v_mov_b32_e32 v125, v5
	v_mov_b32_e32 v124, v5
	v_mov_b32_e32 v123, v5
	v_mov_b32_e32 v122, v5
	v_mov_b32_e32 v129, v5
	v_mov_b32_e32 v128, v5
	v_mov_b32_e32 v127, v5
	v_mov_b32_e32 v126, v5
	s_branch .LBB0_640
.Lgemm_skip_zero_b:
	v_mov_b32_e32 v5, 0
	v_mov_b32_e32 v4, v5
	v_mov_b32_e32 v3, v5
	v_mov_b32_e32 v2, v5
	v_mov_b32_e32 v9, v5
	v_mov_b32_e32 v8, v5
	v_mov_b32_e32 v7, v5
	v_mov_b32_e32 v6, v5
	v_mov_b32_e32 v13, v5
	v_mov_b32_e32 v12, v5
	v_mov_b32_e32 v11, v5
	v_mov_b32_e32 v10, v5
	v_mov_b32_e32 v17, v5
	v_mov_b32_e32 v16, v5
	v_mov_b32_e32 v15, v5
	v_mov_b32_e32 v14, v5
	v_mov_b32_e32 v25, v5
	v_mov_b32_e32 v24, v5
	v_mov_b32_e32 v23, v5
	v_mov_b32_e32 v22, v5
	v_mov_b32_e32 v33, v5
	v_mov_b32_e32 v32, v5
	v_mov_b32_e32 v31, v5
	v_mov_b32_e32 v30, v5
	v_mov_b32_e32 v37, v5
	v_mov_b32_e32 v36, v5
	v_mov_b32_e32 v35, v5
	v_mov_b32_e32 v34, v5
	v_mov_b32_e32 v45, v5
	v_mov_b32_e32 v44, v5
	v_mov_b32_e32 v43, v5
	v_mov_b32_e32 v42, v5
	v_mov_b32_e32 v21, v5
	v_mov_b32_e32 v20, v5
	v_mov_b32_e32 v19, v5
	v_mov_b32_e32 v18, v5
	v_mov_b32_e32 v29, v5
	v_mov_b32_e32 v28, v5
	v_mov_b32_e32 v27, v5
	v_mov_b32_e32 v26, v5
	v_mov_b32_e32 v41, v5
	v_mov_b32_e32 v40, v5
	v_mov_b32_e32 v39, v5
	v_mov_b32_e32 v38, v5
	v_mov_b32_e32 v49, v5
	v_mov_b32_e32 v48, v5
	v_mov_b32_e32 v47, v5
	v_mov_b32_e32 v46, v5
	v_mov_b32_e32 v53, v5
	v_mov_b32_e32 v52, v5
	v_mov_b32_e32 v51, v5
	v_mov_b32_e32 v50, v5
	v_mov_b32_e32 v57, v5
	v_mov_b32_e32 v56, v5
	v_mov_b32_e32 v55, v5
	v_mov_b32_e32 v54, v5
	v_mov_b32_e32 v61, v5
	v_mov_b32_e32 v60, v5
	v_mov_b32_e32 v59, v5
	v_mov_b32_e32 v58, v5
	v_mov_b32_e32 v65, v5
	v_mov_b32_e32 v64, v5
	v_mov_b32_e32 v63, v5
	v_mov_b32_e32 v62, v5
	v_mov_b32_e32 v69, v5
	v_mov_b32_e32 v68, v5
	v_mov_b32_e32 v67, v5
	v_mov_b32_e32 v66, v5
	v_mov_b32_e32 v73, v5
	v_mov_b32_e32 v72, v5
	v_mov_b32_e32 v71, v5
	v_mov_b32_e32 v70, v5
	v_mov_b32_e32 v77, v5
	v_mov_b32_e32 v76, v5
	v_mov_b32_e32 v75, v5
	v_mov_b32_e32 v74, v5
	v_mov_b32_e32 v81, v5
	v_mov_b32_e32 v80, v5
	v_mov_b32_e32 v79, v5
	v_mov_b32_e32 v78, v5
	v_mov_b32_e32 v85, v5
	v_mov_b32_e32 v84, v5
	v_mov_b32_e32 v83, v5
	v_mov_b32_e32 v82, v5
	v_mov_b32_e32 v89, v5
	v_mov_b32_e32 v88, v5
	v_mov_b32_e32 v87, v5
	v_mov_b32_e32 v86, v5
	v_mov_b32_e32 v93, v5
	v_mov_b32_e32 v92, v5
	v_mov_b32_e32 v91, v5
	v_mov_b32_e32 v90, v5
	v_mov_b32_e32 v97, v5
	v_mov_b32_e32 v96, v5
	v_mov_b32_e32 v95, v5
	v_mov_b32_e32 v94, v5
	v_mov_b32_e32 v101, v5
	v_mov_b32_e32 v100, v5
	v_mov_b32_e32 v99, v5
	v_mov_b32_e32 v98, v5
	v_mov_b32_e32 v105, v5
	v_mov_b32_e32 v104, v5
	v_mov_b32_e32 v103, v5
	v_mov_b32_e32 v102, v5
	v_mov_b32_e32 v109, v5
	v_mov_b32_e32 v108, v5
	v_mov_b32_e32 v107, v5
	v_mov_b32_e32 v106, v5
	v_mov_b32_e32 v113, v5
	v_mov_b32_e32 v112, v5
	v_mov_b32_e32 v111, v5
	v_mov_b32_e32 v110, v5
	v_mov_b32_e32 v117, v5
	v_mov_b32_e32 v116, v5
	v_mov_b32_e32 v115, v5
	v_mov_b32_e32 v114, v5
	v_mov_b32_e32 v121, v5
	v_mov_b32_e32 v120, v5
	v_mov_b32_e32 v119, v5
	v_mov_b32_e32 v118, v5
	v_mov_b32_e32 v129, v5
	v_mov_b32_e32 v128, v5
	v_mov_b32_e32 v127, v5
	v_mov_b32_e32 v126, v5
	v_mov_b32_e32 v125, v5
	v_mov_b32_e32 v124, v5
	v_mov_b32_e32 v123, v5
	v_mov_b32_e32 v122, v5
	s_branch .LBB0_627

.LBB0_637:
	s_and_b64 s[2:3], s[8:9], exec
	v_readlane_b32 s2, v255, 26
	v_readlane_b32 s4, v255, 30
	v_readlane_b32 s3, v255, 27
	v_readlane_b32 s5, v255, 31
	s_cselect_b32 s24, s5, s3
	s_cselect_b32 s28, s4, s2
	v_readlane_b32 s2, v255, 24
	v_readlane_b32 s4, v255, 32
	v_readlane_b32 s3, v255, 25
	v_readlane_b32 s5, v255, 33
	s_cselect_b32 s29, s5, s3
	s_cselect_b32 s34, s4, s2
	v_readlane_b32 s2, v255, 23
	v_readlane_b32 s3, v255, 43
	s_cselect_b32 s14, s3, s2
	v_readlane_b32 s2, v255, 39
	s_cselect_b32 s39, s2, 0
	v_readlane_b32 s2, v255, 18
	v_readlane_b32 s3, v255, 40
	s_cselect_b32 s44, s3, s2
	s_lshl_b32 s45, s15, 8
	s_mul_i32 s2, s15, 0xfe
	s_add_i32 s45, s45, s39
	s_lshl_b32 s6, s47, 8
	s_add_i32 s4, s2, -1
	s_cmp_eq_u32 s44, 7
	s_cselect_b64 vcc, -1, 0
	s_and_b64 s[2:3], vcc, exec
	s_cselect_b32 s2, 0, s45
	s_cselect_b32 s40, s4, 0
	s_ashr_i32 s3, s2, 31
	v_mov_b32_e32 v175, v163
	s_mul_i32 s3, s3, s14
	s_mul_hi_u32 s4, s2, s14
	s_ashr_i32 s7, s6, 31
	s_add_i32 s3, s4, s3
	s_waitcnt vmcnt(1)
	v_ashrrev_i32_e32 v10, 6, v175
	s_waitcnt vmcnt(0)
	v_bfe_u32 v14, v175, 3, 3
	s_mul_i32 s2, s2, s14
	s_mul_i32 s4, s7, s14
	s_mul_hi_u32 s5, s6, s14
	v_lshl_or_b32 v6, v10, 5, v14
	s_add_i32 s5, s5, s4
	v_and_b32_e32 v0, 63, v175
	s_lshl_b64 s[2:3], s[2:3], 1
	s_mul_i32 s4, s6, s14
	s_add_u32 s2, s28, s2
	v_lshlrev_b32_e32 v176, 4, v0
	v_add_u32_e32 v0, s40, v6
	s_addc_u32 s3, s24, s3
	s_lshl_b64 s[4:5], s[4:5], 1
	v_med3_i32 v0, v0, 0, v211
	s_add_u32 s4, s34, s4
	v_cndmask_b32_e32 v0, v6, v0, vcc
	s_addc_u32 s5, s29, s5
	v_bfe_u32 v223, v175, 4, 2
	v_mad_u64_u32 v[166:167], s[28:29], v0, s14, 0
	v_xor_b32_e32 v4, v223, v175
	v_ashrrev_i32_e32 v2, 31, v0
	v_mov_b32_e32 v0, v167
	v_mad_u64_u32 v[2:3], s[28:29], v2, s14, v[0:1]
	v_lshlrev_b32_e32 v0, 3, v4
	v_lshlrev_b32_e32 v15, 2, v10
	v_and_b32_e32 v0, 56, v0
	v_lshlrev_b32_e32 v177, 12, v10
	v_lshlrev_b32_e32 v130, 1, v0
	v_ashrrev_i32_e32 v0, 31, v10
	v_or_b32_e32 v17, v176, v177
	v_or_b32_e32 v18, 1, v15
	v_and_b32_e32 v174, 3, v10
	v_mul_lo_u32 v16, v0, s14
	v_readfirstlane_b32 s15, v17
	v_add_u32_e32 v0, 0x8000, v17
	v_lshl_or_b32 v10, v18, 3, v14
	v_mov_b32_e32 v167, v2
	v_mad_u64_u32 v[168:169], s[28:29], v6, s14, 0
	s_mov_b32 m0, s15
	v_readfirstlane_b32 s15, v0
	v_add_u32_e32 v0, s40, v10
	v_lshl_add_u64 v[2:3], v[166:167], 1, s[2:3]
	v_mov_b32_e32 v131, v1
	v_add_u32_e32 v169, v169, v16
	v_med3_i32 v0, v0, 0, v211
	v_lshl_add_u64 v[4:5], v[2:3], 0, v[130:131]
	v_lshl_add_u64 v[6:7], v[168:169], 1, s[4:5]
	v_cndmask_b32_e32 v0, v10, v0, vcc
	v_lshl_add_u64 v[8:9], v[6:7], 0, v[130:131]
	global_load_lds_dwordx4 v[4:5], off
	s_mov_b32 m0, s15
	v_lshrrev_b32_e32 v4, 1, v10
	v_mad_u64_u32 v[170:171], s[28:29], v0, s14, 0
	global_load_lds_dwordx4 v[8:9], off
	v_xor_b32_e32 v8, v4, v175
	v_ashrrev_i32_e32 v4, 31, v0
	v_mov_b32_e32 v0, v171
	v_mad_u64_u32 v[4:5], s[28:29], v4, s14, v[0:1]
	v_lshlrev_b32_e32 v0, 3, v8
	v_lshlrev_b32_e32 v178, 10, v18
	v_mov_b32_e32 v171, v4
	v_and_b32_e32 v0, 56, v0
	v_mad_u64_u32 v[172:173], s[28:29], v10, s14, 0
	v_or_b32_e32 v18, v176, v178
	v_lshl_add_u64 v[4:5], v[170:171], 1, s[2:3]
	v_lshlrev_b32_e32 v132, 1, v0
	v_mov_b32_e32 v133, v1
	v_add_u32_e32 v173, v173, v16
	v_readfirstlane_b32 s15, v18
	v_add_u32_e32 v0, 0x8000, v18
	v_lshl_add_u64 v[8:9], v[4:5], 0, v[132:133]
	v_lshl_add_u64 v[10:11], v[172:173], 1, s[4:5]
	s_mov_b32 m0, s15
	v_readfirstlane_b32 s15, v0
	s_waitcnt lgkmcnt(0)
	v_lshl_add_u64 v[12:13], v[10:11], 0, v[132:133]
	global_load_lds_dwordx4 v[8:9], off
	s_mov_b32 m0, s15
	v_or_b32_e32 v19, 2, v15
	global_load_lds_dwordx4 v[12:13], off
	v_lshl_or_b32 v12, v19, 3, v14
	v_add_u32_e32 v0, s40, v12
	v_med3_i32 v0, v0, 0, v211
	v_cndmask_b32_e32 v0, v12, v0, vcc
	v_lshrrev_b32_e32 v8, 1, v12
	v_mad_u64_u32 v[154:155], s[28:29], v0, s14, 0
	v_xor_b32_e32 v13, v8, v175
	v_ashrrev_i32_e32 v8, 31, v0
	v_mov_b32_e32 v0, v155
	v_mad_u64_u32 v[8:9], s[28:29], v8, s14, v[0:1]
	v_lshlrev_b32_e32 v0, 3, v13
	v_lshlrev_b32_e32 v179, 10, v19
	v_mov_b32_e32 v155, v8
	v_and_b32_e32 v0, 56, v0
	v_or_b32_e32 v19, v176, v179
	v_lshl_add_u64 v[8:9], v[154:155], 1, s[2:3]
	v_lshlrev_b32_e32 v0, 1, v0
	v_readfirstlane_b32 s15, v19
	v_lshl_add_u64 v[8:9], v[8:9], 0, v[0:1]
	v_mad_u64_u32 v[156:157], s[28:29], v12, s14, 0
	s_mov_b32 m0, s15
	v_add_u32_e32 v157, v157, v16
	global_load_lds_dwordx4 v[8:9], off
	v_add_u32_e32 v8, 0x8000, v19
	v_lshl_add_u64 v[12:13], v[156:157], 1, s[4:5]
	v_readfirstlane_b32 s15, v8
	v_lshl_add_u64 v[12:13], v[12:13], 0, v[0:1]
	s_mov_b32 m0, s15
	v_or_b32_e32 v15, 3, v15
	global_load_lds_dwordx4 v[12:13], off
	v_lshl_or_b32 v12, v15, 3, v14
	v_add_u32_e32 v8, s40, v12
	v_med3_i32 v8, v8, 0, v211
	v_cndmask_b32_e32 v8, v12, v8, vcc
	v_lshrrev_b32_e32 v9, 1, v12
	v_mad_u64_u32 v[158:159], s[28:29], v8, s14, 0
	v_xor_b32_e32 v13, v9, v175
	v_ashrrev_i32_e32 v9, 31, v8
	v_mov_b32_e32 v8, v159
	v_mad_u64_u32 v[8:9], s[28:29], v9, s14, v[8:9]
	v_lshlrev_b32_e32 v13, 3, v13
	v_lshlrev_b32_e32 v180, 10, v15
	v_mov_b32_e32 v159, v8
	v_and_b32_e32 v13, 56, v13
	v_or_b32_e32 v14, v176, v180
	v_lshl_add_u64 v[8:9], v[158:159], 1, s[2:3]
	v_lshlrev_b32_e32 v160, 1, v13
	v_mov_b32_e32 v161, v1
	v_readfirstlane_b32 s15, v14
	v_lshl_add_u64 v[8:9], v[8:9], 0, v[160:161]
	v_mad_u64_u32 v[164:165], s[28:29], v12, s14, 0
	s_mov_b32 m0, s15
	v_add_u32_e32 v165, v165, v16
	global_load_lds_dwordx4 v[8:9], off
	v_add_u32_e32 v8, 0x8000, v14
	s_cmpk_gt_u32 s14, 0x7f
	v_lshl_add_u64 v[12:13], v[164:165], 1, s[4:5]
	v_readfirstlane_b32 s15, v8
	s_cselect_b32 s34, 0x80, 0
	v_add_u32_e32 v8, 0x10000, v17
	v_lshl_add_u64 v[12:13], v[12:13], 0, v[160:161]
	s_mov_b32 m0, s15
	v_lshl_add_u64 v[2:3], v[2:3], 0, s[34:35]
	v_readfirstlane_b32 s15, v8
	global_load_lds_dwordx4 v[12:13], off
	v_lshl_add_u64 v[2:3], v[2:3], 0, v[130:131]
	s_mov_b32 m0, s15
	v_mov_b32_e32 v127, 0
	v_mov_b32_e32 v128, 0
	v_mov_b32_e32 v129, 0
	v_mov_b32_e32 v122, 0
	v_mov_b32_e32 v123, 0
	v_mov_b32_e32 v124, 0
	v_mov_b32_e32 v125, 0
	v_mov_b32_e32 v118, 0
	v_mov_b32_e32 v119, 0
	v_mov_b32_e32 v120, 0
	v_mov_b32_e32 v121, 0
	v_mov_b32_e32 v114, 0
	v_mov_b32_e32 v115, 0
	v_mov_b32_e32 v116, 0
	v_mov_b32_e32 v117, 0
	v_mov_b32_e32 v110, 0
	v_mov_b32_e32 v111, 0
	v_mov_b32_e32 v112, 0
	v_mov_b32_e32 v113, 0
	v_mov_b32_e32 v106, 0
	v_mov_b32_e32 v107, 0
	v_mov_b32_e32 v108, 0
	v_mov_b32_e32 v109, 0
	v_mov_b32_e32 v102, 0
	v_mov_b32_e32 v103, 0
	v_mov_b32_e32 v104, 0
	v_mov_b32_e32 v105, 0
	v_mov_b32_e32 v98, 0
	v_mov_b32_e32 v99, 0
	v_mov_b32_e32 v100, 0
	v_mov_b32_e32 v101, 0
	v_mov_b32_e32 v94, 0
	v_mov_b32_e32 v95, 0
	v_mov_b32_e32 v96, 0
	v_mov_b32_e32 v97, 0
	v_mov_b32_e32 v90, 0
	v_mov_b32_e32 v91, 0
	v_mov_b32_e32 v92, 0
	v_mov_b32_e32 v93, 0
	v_mov_b32_e32 v86, 0
	v_mov_b32_e32 v87, 0
	v_mov_b32_e32 v88, 0
	v_mov_b32_e32 v89, 0
	v_mov_b32_e32 v82, 0
	v_mov_b32_e32 v83, 0
	v_mov_b32_e32 v84, 0
	v_mov_b32_e32 v85, 0
	v_mov_b32_e32 v78, 0
	v_mov_b32_e32 v79, 0
	v_mov_b32_e32 v80, 0
	v_mov_b32_e32 v81, 0
	v_mov_b32_e32 v74, 0
	v_mov_b32_e32 v75, 0
	v_mov_b32_e32 v76, 0
	v_mov_b32_e32 v77, 0
	v_mov_b32_e32 v70, 0
	v_mov_b32_e32 v71, 0
	v_mov_b32_e32 v72, 0
	v_mov_b32_e32 v73, 0
	v_mov_b32_e32 v66, 0
	v_mov_b32_e32 v67, 0
	v_mov_b32_e32 v68, 0
	v_mov_b32_e32 v69, 0
	v_mov_b32_e32 v62, 0
	v_mov_b32_e32 v63, 0
	v_mov_b32_e32 v64, 0
	v_mov_b32_e32 v65, 0
	v_mov_b32_e32 v58, 0
	v_mov_b32_e32 v59, 0
	v_mov_b32_e32 v60, 0
	v_mov_b32_e32 v61, 0
	v_mov_b32_e32 v54, 0
	v_mov_b32_e32 v55, 0
	v_mov_b32_e32 v56, 0
	v_mov_b32_e32 v57, 0
	v_mov_b32_e32 v50, 0
	v_mov_b32_e32 v51, 0
	v_mov_b32_e32 v52, 0
	v_mov_b32_e32 v53, 0
	v_mov_b32_e32 v46, 0
	v_mov_b32_e32 v47, 0
	v_mov_b32_e32 v48, 0
	v_mov_b32_e32 v49, 0
	v_mov_b32_e32 v42, 0
	v_mov_b32_e32 v43, 0
	v_mov_b32_e32 v44, 0
	v_mov_b32_e32 v45, 0
	v_mov_b32_e32 v34, 0
	v_mov_b32_e32 v35, 0
	v_mov_b32_e32 v36, 0
	v_mov_b32_e32 v37, 0
	v_mov_b32_e32 v30, 0
	v_mov_b32_e32 v31, 0
	v_mov_b32_e32 v32, 0
	v_mov_b32_e32 v33, 0
	v_mov_b32_e32 v38, 0
	v_mov_b32_e32 v39, 0
	v_mov_b32_e32 v40, 0
	v_mov_b32_e32 v41, 0
	v_mov_b32_e32 v26, 0
	v_mov_b32_e32 v27, 0
	v_mov_b32_e32 v28, 0
	v_mov_b32_e32 v29, 0
	v_mov_b32_e32 v22, 0
	v_mov_b32_e32 v23, 0
	v_mov_b32_e32 v24, 0
	v_mov_b32_e32 v25, 0
	v_mov_b32_e32 v19, 0
	v_mov_b32_e32 v20, 0
	v_mov_b32_e32 v21, 0
	v_mov_b32_e32 v14, 0
	v_mov_b32_e32 v15, 0
	v_mov_b32_e32 v16, 0
	v_mov_b32_e32 v12, 0
	v_mov_b32_e32 v13, 0
	s_waitcnt vmcnt(0)
	s_waitcnt vmcnt(0) lgkmcnt(0)
	s_barrier
	global_load_lds_dwordx4 v[2:3], off
	v_add_u32_e32 v2, 0x18000, v17
	v_lshl_add_u64 v[6:7], v[6:7], 0, s[34:35]
	v_readfirstlane_b32 s15, v2
	v_lshl_add_u64 v[6:7], v[6:7], 0, v[130:131]
	s_mov_b32 m0, s15
	v_lshl_add_u64 v[2:3], v[4:5], 0, s[34:35]
	global_load_lds_dwordx4 v[6:7], off
	v_add_u32_e32 v6, 0x10000, v18
	v_lshl_add_u64 v[2:3], v[2:3], 0, v[132:133]
	v_readfirstlane_b32 s15, v6
	s_mov_b32 m0, s15
	v_lshl_add_u64 v[4:5], v[10:11], 0, s[34:35]
	global_load_lds_dwordx4 v[2:3], off
	v_add_u32_e32 v2, 0x18000, v18
	v_lshl_add_u64 v[4:5], v[4:5], 0, v[132:133]
	v_readfirstlane_b32 s15, v2
	s_mov_b32 m0, s15
	v_and_b32_e32 v134, 15, v175
	global_load_lds_dwordx4 v[4:5], off
	v_ashrrev_i32_e32 v2, 1, v175
	s_movk_i32 s15, 0xff80
	v_mov_b32_e32 v5, 0
	v_and_or_b32 v225, v2, s15, v134
	v_lshlrev_b32_e32 v224, 6, v174
	s_cmp_lt_u32 s14, 64
	v_readlane_b32 s51, v255, 37
	v_readlane_b32 s52, v255, 38
	s_cbranch_scc1 .Lgemm_skip_zero_a
	v_lshrrev_b32_e32 v10, 1, v134
	v_or_b32_e32 v2, v224, v134
	v_lshlrev_b32_e32 v182, 7, v2
	v_xor_b32_e32 v2, v223, v10
	v_lshlrev_b32_e32 v181, 7, v225
	v_lshlrev_b32_e32 v183, 4, v2
	v_or_b32_e32 v11, v181, v183
	ds_read_b128 v[146:149], v11 offset:2048
	ds_read_b128 v[150:153], v11
	v_or_b32_e32 v11, v182, v183
	v_lshl_add_u64 v[2:3], s[4:5], 0, v[132:133]
	v_lshl_add_u64 v[4:5], s[2:3], 0, v[132:133]
	v_lshl_add_u64 v[6:7], s[4:5], 0, v[130:131]
	v_lshl_add_u64 v[8:9], s[2:3], 0, v[130:131]
	ds_read_b128 v[130:133], v11 offset:38912
	ds_read_b128 v[134:137], v11 offset:36864
	ds_read_b128 v[138:141], v11 offset:34816
	ds_read_b128 v[142:145], v11 offset:32768
	s_lshr_b32 s14, s14, 6
	v_bitop3_b32 v10, v223, v10, 4 bitop3:0x36
	v_mov_b32_e32 v126, 0
	s_add_i32 s15, s14, -1
	v_lshlrev_b32_e32 v184, 4, v10
	v_lshl_add_u64 v[166:167], v[166:167], 1, v[8:9]
	v_lshl_add_u64 v[168:169], v[168:169], 1, v[6:7]
	v_lshl_add_u64 v[170:171], v[170:171], 1, v[4:5]
	v_lshl_add_u64 v[172:173], v[172:173], 1, v[2:3]
	s_mov_b32 s24, 0
	s_mov_b32 s28, 0
	v_mov_b32_e32 v18, v126
	v_mov_b32_e32 v17, v126
	v_mov_b32_e32 v10, v126
	v_mov_b32_e32 v11, v126
	v_mov_b32_e32 v6, v126
	v_mov_b32_e32 v7, v126
	v_mov_b32_e32 v8, v126
	v_mov_b32_e32 v9, v126
	v_mov_b32_e32 v2, v126
	v_mov_b32_e32 v3, v126
	v_mov_b32_e32 v4, v126
	v_mov_b32_e32 v5, v126

.LBB0_1308:
	v_lshlrev_b64 v[42:43], 12, v[42:43]
	v_lshl_add_u64 v[42:43], v[44:45], 0, v[42:43]
	v_lshl_add_u64 v[42:43], v[42:43], 0, v[0:1]
	global_load_dwordx4 v[62:65], v[42:43], off
	global_load_dwordx4 v[58:61], v[42:43], off offset:1024
	global_load_dwordx4 v[50:53], v[42:43], off offset:2048
	s_nop 0
	global_load_dwordx4 v[42:45], v[42:43], off offset:3072
	v_cmp_lt_i32_e32 vcc, s0, v96
	s_and_b64 s[14:15], s[8:9], vcc
	s_and_saveexec_b64 s[4:5], s[14:15]
	s_cbranch_execz .LBB0_1287
	s_mov_b32 s14, 0x800000
	s_mov_b32 s15, 0
	v_mov_b32_e32 v89, v1
	v_add_u32_e32 v242, 0, v88
	v_mov_b32_e32 v243, v1
	v_lshlrev_b64 v[242:243], 12, v[242:243]
	v_lshl_add_u64 v[224:225], v[80:81], 0, v[242:243]
	v_add_u32_e32 v242, 0, v96
	v_mov_b32_e32 v243, v1
	v_lshlrev_b64 v[242:243], 12, v[242:243]
	v_lshl_add_u64 v[232:233], v[74:75], 0, v[242:243]
	v_add_u32_e32 v242, 1, v88
	v_mov_b32_e32 v243, v1
	v_lshlrev_b64 v[242:243], 12, v[242:243]
	v_lshl_add_u64 v[226:227], v[80:81], 0, v[242:243]
	v_add_u32_e32 v242, 1, v96
	v_mov_b32_e32 v243, v1
	v_lshlrev_b64 v[242:243], 12, v[242:243]
	v_lshl_add_u64 v[234:235], v[74:75], 0, v[242:243]
	v_add_u32_e32 v242, 2, v88
	v_mov_b32_e32 v243, v1
	v_lshlrev_b64 v[242:243], 12, v[242:243]
	v_lshl_add_u64 v[228:229], v[80:81], 0, v[242:243]
	v_add_u32_e32 v242, 2, v96
	v_mov_b32_e32 v243, v1
	v_lshlrev_b64 v[242:243], 12, v[242:243]
	v_lshl_add_u64 v[236:237], v[74:75], 0, v[242:243]
	v_add_u32_e32 v242, 3, v88
	v_mov_b32_e32 v243, v1
	v_lshlrev_b64 v[242:243], 12, v[242:243]
	v_lshl_add_u64 v[230:231], v[80:81], 0, v[242:243]
	v_add_u32_e32 v242, 3, v96
	v_mov_b32_e32 v243, v1
	v_lshlrev_b64 v[242:243], 12, v[242:243]
	v_lshl_add_u64 v[238:239], v[74:75], 0, v[242:243]
	global_load_dwordx4 v[66:69], v[78:79], off
	v_mov_b64_e32 v[240:241], v[224:225]
	global_load_dwordx4 v[104:107], v[240:241], off
	v_lshl_add_u64 v[240:241], v[240:241], 0, s[14:15]
	global_load_dwordx4 v[108:111], v[240:241], off
	v_lshl_add_u64 v[240:241], v[240:241], 0, s[14:15]
	global_load_dwordx4 v[112:115], v[240:241], off
	v_lshl_add_u64 v[240:241], v[240:241], 0, s[14:15]
	global_load_dwordx4 v[116:119], v[240:241], off
	v_lshl_add_u64 v[240:241], v[240:241], 0, s[14:15]
	global_load_dwordx4 v[120:123], v[240:241], off
	v_lshl_add_u64 v[240:241], v[240:241], 0, s[14:15]
	global_load_dwordx4 v[124:127], v[240:241], off
	v_lshl_add_u64 v[240:241], v[240:241], 0, s[14:15]
	global_load_dwordx4 v[128:131], v[240:241], off
	v_lshl_add_u64 v[240:241], v[240:241], 0, s[14:15]
	global_load_dwordx4 v[132:135], v[240:241], off
	v_mov_b64_e32 v[240:241], v[226:227]
	global_load_dwordx4 v[136:139], v[240:241], off
	v_lshl_add_u64 v[240:241], v[240:241], 0, s[14:15]
	global_load_dwordx4 v[140:143], v[240:241], off
	v_lshl_add_u64 v[240:241], v[240:241], 0, s[14:15]
	global_load_dwordx4 v[144:147], v[240:241], off
	v_lshl_add_u64 v[240:241], v[240:241], 0, s[14:15]
	global_load_dwordx4 v[148:151], v[240:241], off
	v_lshl_add_u64 v[240:241], v[240:241], 0, s[14:15]
	global_load_dwordx4 v[152:155], v[240:241], off
	v_lshl_add_u64 v[240:241], v[240:241], 0, s[14:15]
	global_load_dwordx4 v[156:159], v[240:241], off
	v_lshl_add_u64 v[240:241], v[240:241], 0, s[14:15]
	global_load_dwordx4 v[164:167], v[240:241], off
	v_lshl_add_u64 v[240:241], v[240:241], 0, s[14:15]
	global_load_dwordx4 v[168:171], v[240:241], off
	s_waitcnt vmcnt(15)
	v_pk_add_f32 v[172:173], v[104:105], 0 op_sel_hi:[1,0]
	v_pk_add_f32 v[174:175], v[106:107], 0 op_sel_hi:[1,0]
	s_waitcnt vmcnt(14)
	v_pk_add_f32 v[172:173], v[172:173], v[108:109]
	v_pk_add_f32 v[174:175], v[174:175], v[110:111]
	s_waitcnt vmcnt(13)
	v_pk_add_f32 v[172:173], v[172:173], v[112:113]
	v_pk_add_f32 v[174:175], v[174:175], v[114:115]
	s_waitcnt vmcnt(12)
	v_pk_add_f32 v[172:173], v[172:173], v[116:117]
	v_pk_add_f32 v[174:175], v[174:175], v[118:119]
	s_waitcnt vmcnt(11)
	v_pk_add_f32 v[172:173], v[172:173], v[120:121]
	v_pk_add_f32 v[174:175], v[174:175], v[122:123]
	s_waitcnt vmcnt(10)
	v_pk_add_f32 v[172:173], v[172:173], v[124:125]
	v_pk_add_f32 v[174:175], v[174:175], v[126:127]
	s_waitcnt vmcnt(9)
	v_pk_add_f32 v[172:173], v[172:173], v[128:129]
	v_pk_add_f32 v[174:175], v[174:175], v[130:131]
	s_waitcnt vmcnt(8)
	v_pk_add_f32 v[172:173], v[172:173], v[132:133]
	v_pk_add_f32 v[174:175], v[174:175], v[134:135]
	s_nop 0
	v_pk_fma_f32 v[34:35], v[66:67], v[172:173], v[34:35]
	v_pk_fma_f32 v[36:37], v[68:69], v[174:175], v[36:37]
	global_store_dwordx4 v[232:233], v[34:37], off
	s_waitcnt vmcnt(8)
	v_pk_add_f32 v[184:185], v[136:137], 0 op_sel_hi:[1,0]
	v_pk_add_f32 v[186:187], v[138:139], 0 op_sel_hi:[1,0]
	s_waitcnt vmcnt(7)
	v_pk_add_f32 v[184:185], v[184:185], v[140:141]
	v_pk_add_f32 v[186:187], v[186:187], v[142:143]
	s_waitcnt vmcnt(6)
	v_pk_add_f32 v[184:185], v[184:185], v[144:145]
	v_pk_add_f32 v[186:187], v[186:187], v[146:147]
	s_waitcnt vmcnt(5)
	v_pk_add_f32 v[184:185], v[184:185], v[148:149]
	v_pk_add_f32 v[186:187], v[186:187], v[150:151]
	s_waitcnt vmcnt(4)
	v_pk_add_f32 v[184:185], v[184:185], v[152:153]
	v_pk_add_f32 v[186:187], v[186:187], v[154:155]
	s_waitcnt vmcnt(3)
	v_pk_add_f32 v[184:185], v[184:185], v[156:157]
	v_pk_add_f32 v[186:187], v[186:187], v[158:159]
	s_waitcnt vmcnt(2)
	v_pk_add_f32 v[184:185], v[184:185], v[164:165]
	v_pk_add_f32 v[186:187], v[186:187], v[166:167]
	s_waitcnt vmcnt(1)
	v_pk_add_f32 v[184:185], v[184:185], v[168:169]
	v_pk_add_f32 v[186:187], v[186:187], v[170:171]
	s_nop 0
	v_pk_fma_f32 v[46:47], v[66:67], v[184:185], v[46:47]
	v_pk_fma_f32 v[48:49], v[68:69], v[186:187], v[48:49]
	global_store_dwordx4 v[234:235], v[46:49], off
	v_mov_b64_e32 v[240:241], v[228:229]
	global_load_dwordx4 v[104:107], v[240:241], off
	v_lshl_add_u64 v[240:241], v[240:241], 0, s[14:15]
	global_load_dwordx4 v[108:111], v[240:241], off
	v_lshl_add_u64 v[240:241], v[240:241], 0, s[14:15]
	global_load_dwordx4 v[112:115], v[240:241], off
	v_lshl_add_u64 v[240:241], v[240:241], 0, s[14:15]
	global_load_dwordx4 v[116:119], v[240:241], off
	v_lshl_add_u64 v[240:241], v[240:241], 0, s[14:15]
	global_load_dwordx4 v[120:123], v[240:241], off
	v_lshl_add_u64 v[240:241], v[240:241], 0, s[14:15]
	global_load_dwordx4 v[124:127], v[240:241], off
	v_lshl_add_u64 v[240:241], v[240:241], 0, s[14:15]
	global_load_dwordx4 v[128:131], v[240:241], off
	v_lshl_add_u64 v[240:241], v[240:241], 0, s[14:15]
	global_load_dwordx4 v[132:135], v[240:241], off
	v_mov_b64_e32 v[240:241], v[230:231]
	global_load_dwordx4 v[136:139], v[240:241], off
	v_lshl_add_u64 v[240:241], v[240:241], 0, s[14:15]
	global_load_dwordx4 v[140:143], v[240:241], off
	v_lshl_add_u64 v[240:241], v[240:241], 0, s[14:15]
	global_load_dwordx4 v[144:147], v[240:241], off
	v_lshl_add_u64 v[240:241], v[240:241], 0, s[14:15]
	global_load_dwordx4 v[148:151], v[240:241], off
	v_lshl_add_u64 v[240:241], v[240:241], 0, s[14:15]
	global_load_dwordx4 v[152:155], v[240:241], off
	v_lshl_add_u64 v[240:241], v[240:241], 0, s[14:15]
	global_load_dwordx4 v[156:159], v[240:241], off
	v_lshl_add_u64 v[240:241], v[240:241], 0, s[14:15]
	global_load_dwordx4 v[164:167], v[240:241], off
	v_lshl_add_u64 v[240:241], v[240:241], 0, s[14:15]
	global_load_dwordx4 v[168:171], v[240:241], off
	s_waitcnt vmcnt(15)
	v_pk_add_f32 v[172:173], v[104:105], 0 op_sel_hi:[1,0]
	v_pk_add_f32 v[174:175], v[106:107], 0 op_sel_hi:[1,0]
	s_waitcnt vmcnt(14)
	v_pk_add_f32 v[172:173], v[172:173], v[108:109]
	v_pk_add_f32 v[174:175], v[174:175], v[110:111]
	s_waitcnt vmcnt(13)
	v_pk_add_f32 v[172:173], v[172:173], v[112:113]
	v_pk_add_f32 v[174:175], v[174:175], v[114:115]
	s_waitcnt vmcnt(12)
	v_pk_add_f32 v[172:173], v[172:173], v[116:117]
	v_pk_add_f32 v[174:175], v[174:175], v[118:119]
	s_waitcnt vmcnt(11)
	v_pk_add_f32 v[172:173], v[172:173], v[120:121]
	v_pk_add_f32 v[174:175], v[174:175], v[122:123]
	s_waitcnt vmcnt(10)
	v_pk_add_f32 v[172:173], v[172:173], v[124:125]
	v_pk_add_f32 v[174:175], v[174:175], v[126:127]
	s_waitcnt vmcnt(9)
	v_pk_add_f32 v[172:173], v[172:173], v[128:129]
	v_pk_add_f32 v[174:175], v[174:175], v[130:131]
	s_waitcnt vmcnt(8)
	v_pk_add_f32 v[172:173], v[172:173], v[132:133]
	v_pk_add_f32 v[174:175], v[174:175], v[134:135]
	s_nop 0
	v_pk_fma_f32 v[54:55], v[66:67], v[172:173], v[54:55]
	v_pk_fma_f32 v[56:57], v[68:69], v[174:175], v[56:57]
	global_store_dwordx4 v[236:237], v[54:57], off
	s_waitcnt vmcnt(8)
	v_pk_add_f32 v[184:185], v[136:137], 0 op_sel_hi:[1,0]
	v_pk_add_f32 v[186:187], v[138:139], 0 op_sel_hi:[1,0]
	s_waitcnt vmcnt(7)
	v_pk_add_f32 v[184:185], v[184:185], v[140:141]
	v_pk_add_f32 v[186:187], v[186:187], v[142:143]
	s_waitcnt vmcnt(6)
	v_pk_add_f32 v[184:185], v[184:185], v[144:145]
	v_pk_add_f32 v[186:187], v[186:187], v[146:147]
	s_waitcnt vmcnt(5)
	v_pk_add_f32 v[184:185], v[184:185], v[148:149]
	v_pk_add_f32 v[186:187], v[186:187], v[150:151]
	s_waitcnt vmcnt(4)
	v_pk_add_f32 v[184:185], v[184:185], v[152:153]
	v_pk_add_f32 v[186:187], v[186:187], v[154:155]
	s_waitcnt vmcnt(3)
	v_pk_add_f32 v[184:185], v[184:185], v[156:157]
	v_pk_add_f32 v[186:187], v[186:187], v[158:159]
	s_waitcnt vmcnt(2)
	v_pk_add_f32 v[184:185], v[184:185], v[164:165]
	v_pk_add_f32 v[186:187], v[186:187], v[166:167]
	s_waitcnt vmcnt(1)
	v_pk_add_f32 v[184:185], v[184:185], v[168:169]
	v_pk_add_f32 v[186:187], v[186:187], v[170:171]
	s_nop 0
	v_pk_fma_f32 v[62:63], v[66:67], v[184:185], v[62:63]
	v_pk_fma_f32 v[64:65], v[68:69], v[186:187], v[64:65]
	global_store_dwordx4 v[238:239], v[62:65], off
	global_load_dwordx4 v[66:69], v[82:83], off
	v_mov_b64_e32 v[240:241], v[224:225]
	global_load_dwordx4 v[104:107], v[240:241], off offset:1024
	v_lshl_add_u64 v[240:241], v[240:241], 0, s[14:15]
	global_load_dwordx4 v[108:111], v[240:241], off offset:1024
	v_lshl_add_u64 v[240:241], v[240:241], 0, s[14:15]
	global_load_dwordx4 v[112:115], v[240:241], off offset:1024
	v_lshl_add_u64 v[240:241], v[240:241], 0, s[14:15]
	global_load_dwordx4 v[116:119], v[240:241], off offset:1024
	v_lshl_add_u64 v[240:241], v[240:241], 0, s[14:15]
	global_load_dwordx4 v[120:123], v[240:241], off offset:1024
	v_lshl_add_u64 v[240:241], v[240:241], 0, s[14:15]
	global_load_dwordx4 v[124:127], v[240:241], off offset:1024
	v_lshl_add_u64 v[240:241], v[240:241], 0, s[14:15]
	global_load_dwordx4 v[128:131], v[240:241], off offset:1024
	v_lshl_add_u64 v[240:241], v[240:241], 0, s[14:15]
	global_load_dwordx4 v[132:135], v[240:241], off offset:1024
	v_mov_b64_e32 v[240:241], v[226:227]
	global_load_dwordx4 v[136:139], v[240:241], off offset:1024
	v_lshl_add_u64 v[240:241], v[240:241], 0, s[14:15]
	global_load_dwordx4 v[140:143], v[240:241], off offset:1024
	v_lshl_add_u64 v[240:241], v[240:241], 0, s[14:15]
	global_load_dwordx4 v[144:147], v[240:241], off offset:1024
	v_lshl_add_u64 v[240:241], v[240:241], 0, s[14:15]
	global_load_dwordx4 v[148:151], v[240:241], off offset:1024
	v_lshl_add_u64 v[240:241], v[240:241], 0, s[14:15]
	global_load_dwordx4 v[152:155], v[240:241], off offset:1024
	v_lshl_add_u64 v[240:241], v[240:241], 0, s[14:15]
	global_load_dwordx4 v[156:159], v[240:241], off offset:1024
	v_lshl_add_u64 v[240:241], v[240:241], 0, s[14:15]
	global_load_dwordx4 v[164:167], v[240:241], off offset:1024
	v_lshl_add_u64 v[240:241], v[240:241], 0, s[14:15]
	global_load_dwordx4 v[168:171], v[240:241], off offset:1024
	s_waitcnt vmcnt(15)
	v_pk_add_f32 v[172:173], v[104:105], 0 op_sel_hi:[1,0]
	v_pk_add_f32 v[174:175], v[106:107], 0 op_sel_hi:[1,0]
	s_waitcnt vmcnt(14)
	v_pk_add_f32 v[172:173], v[172:173], v[108:109]
	v_pk_add_f32 v[174:175], v[174:175], v[110:111]
	s_waitcnt vmcnt(13)
	v_pk_add_f32 v[172:173], v[172:173], v[112:113]
	v_pk_add_f32 v[174:175], v[174:175], v[114:115]
	s_waitcnt vmcnt(12)
	v_pk_add_f32 v[172:173], v[172:173], v[116:117]
	v_pk_add_f32 v[174:175], v[174:175], v[118:119]
	s_waitcnt vmcnt(11)
	v_pk_add_f32 v[172:173], v[172:173], v[120:121]
	v_pk_add_f32 v[174:175], v[174:175], v[122:123]
	s_waitcnt vmcnt(10)
	v_pk_add_f32 v[172:173], v[172:173], v[124:125]
	v_pk_add_f32 v[174:175], v[174:175], v[126:127]
	s_waitcnt vmcnt(9)
	v_pk_add_f32 v[172:173], v[172:173], v[128:129]
	v_pk_add_f32 v[174:175], v[174:175], v[130:131]
	s_waitcnt vmcnt(8)
	v_pk_add_f32 v[172:173], v[172:173], v[132:133]
	v_pk_add_f32 v[174:175], v[174:175], v[134:135]
	s_nop 0
	v_pk_fma_f32 v[14:15], v[66:67], v[172:173], v[14:15]
	v_pk_fma_f32 v[16:17], v[68:69], v[174:175], v[16:17]
	global_store_dwordx4 v[232:233], v[14:17], off offset:1024
	s_waitcnt vmcnt(8)
	v_pk_add_f32 v[184:185], v[136:137], 0 op_sel_hi:[1,0]
	v_pk_add_f32 v[186:187], v[138:139], 0 op_sel_hi:[1,0]
	s_waitcnt vmcnt(7)
	v_pk_add_f32 v[184:185], v[184:185], v[140:141]
	v_pk_add_f32 v[186:187], v[186:187], v[142:143]
	s_waitcnt vmcnt(6)
	v_pk_add_f32 v[184:185], v[184:185], v[144:145]
	v_pk_add_f32 v[186:187], v[186:187], v[146:147]
	s_waitcnt vmcnt(5)
	v_pk_add_f32 v[184:185], v[184:185], v[148:149]
	v_pk_add_f32 v[186:187], v[186:187], v[150:151]
	s_waitcnt vmcnt(4)
	v_pk_add_f32 v[184:185], v[184:185], v[152:153]
	v_pk_add_f32 v[186:187], v[186:187], v[154:155]
	s_waitcnt vmcnt(3)
	v_pk_add_f32 v[184:185], v[184:185], v[156:157]
	v_pk_add_f32 v[186:187], v[186:187], v[158:159]
	s_waitcnt vmcnt(2)
	v_pk_add_f32 v[184:185], v[184:185], v[164:165]
	v_pk_add_f32 v[186:187], v[186:187], v[166:167]
	s_waitcnt vmcnt(1)
	v_pk_add_f32 v[184:185], v[184:185], v[168:169]
	v_pk_add_f32 v[186:187], v[186:187], v[170:171]
	s_nop 0
	v_pk_fma_f32 v[26:27], v[66:67], v[184:185], v[26:27]
	v_pk_fma_f32 v[28:29], v[68:69], v[186:187], v[28:29]
	global_store_dwordx4 v[234:235], v[26:29], off offset:1024
	v_mov_b64_e32 v[240:241], v[228:229]
	global_load_dwordx4 v[104:107], v[240:241], off offset:1024
	v_lshl_add_u64 v[240:241], v[240:241], 0, s[14:15]
	global_load_dwordx4 v[108:111], v[240:241], off offset:1024
	v_lshl_add_u64 v[240:241], v[240:241], 0, s[14:15]
	global_load_dwordx4 v[112:115], v[240:241], off offset:1024
	v_lshl_add_u64 v[240:241], v[240:241], 0, s[14:15]
	global_load_dwordx4 v[116:119], v[240:241], off offset:1024
	v_lshl_add_u64 v[240:241], v[240:241], 0, s[14:15]
	global_load_dwordx4 v[120:123], v[240:241], off offset:1024
	v_lshl_add_u64 v[240:241], v[240:241], 0, s[14:15]
	global_load_dwordx4 v[124:127], v[240:241], off offset:1024
	v_lshl_add_u64 v[240:241], v[240:241], 0, s[14:15]
	global_load_dwordx4 v[128:131], v[240:241], off offset:1024
	v_lshl_add_u64 v[240:241], v[240:241], 0, s[14:15]
	global_load_dwordx4 v[132:135], v[240:241], off offset:1024
	v_mov_b64_e32 v[240:241], v[230:231]
	global_load_dwordx4 v[136:139], v[240:241], off offset:1024
	v_lshl_add_u64 v[240:241], v[240:241], 0, s[14:15]
	global_load_dwordx4 v[140:143], v[240:241], off offset:1024
	v_lshl_add_u64 v[240:241], v[240:241], 0, s[14:15]
	global_load_dwordx4 v[144:147], v[240:241], off offset:1024
	v_lshl_add_u64 v[240:241], v[240:241], 0, s[14:15]
	global_load_dwordx4 v[148:151], v[240:241], off offset:1024
	v_lshl_add_u64 v[240:241], v[240:241], 0, s[14:15]
	global_load_dwordx4 v[152:155], v[240:241], off offset:1024
	v_lshl_add_u64 v[240:241], v[240:241], 0, s[14:15]
	global_load_dwordx4 v[156:159], v[240:241], off offset:1024
	v_lshl_add_u64 v[240:241], v[240:241], 0, s[14:15]
	global_load_dwordx4 v[164:167], v[240:241], off offset:1024
	v_lshl_add_u64 v[240:241], v[240:241], 0, s[14:15]
	global_load_dwordx4 v[168:171], v[240:241], off offset:1024
	s_waitcnt vmcnt(15)
	v_pk_add_f32 v[172:173], v[104:105], 0 op_sel_hi:[1,0]
	v_pk_add_f32 v[174:175], v[106:107], 0 op_sel_hi:[1,0]
	s_waitcnt vmcnt(14)
	v_pk_add_f32 v[172:173], v[172:173], v[108:109]
	v_pk_add_f32 v[174:175], v[174:175], v[110:111]
	s_waitcnt vmcnt(13)
	v_pk_add_f32 v[172:173], v[172:173], v[112:113]
	v_pk_add_f32 v[174:175], v[174:175], v[114:115]
	s_waitcnt vmcnt(12)
	v_pk_add_f32 v[172:173], v[172:173], v[116:117]
	v_pk_add_f32 v[174:175], v[174:175], v[118:119]
	s_waitcnt vmcnt(11)
	v_pk_add_f32 v[172:173], v[172:173], v[120:121]
	v_pk_add_f32 v[174:175], v[174:175], v[122:123]
	s_waitcnt vmcnt(10)
	v_pk_add_f32 v[172:173], v[172:173], v[124:125]
	v_pk_add_f32 v[174:175], v[174:175], v[126:127]
	s_waitcnt vmcnt(9)
	v_pk_add_f32 v[172:173], v[172:173], v[128:129]
	v_pk_add_f32 v[174:175], v[174:175], v[130:131]
	s_waitcnt vmcnt(8)
	v_pk_add_f32 v[172:173], v[172:173], v[132:133]
	v_pk_add_f32 v[174:175], v[174:175], v[134:135]
	s_nop 0
	v_pk_fma_f32 v[38:39], v[66:67], v[172:173], v[38:39]
	v_pk_fma_f32 v[40:41], v[68:69], v[174:175], v[40:41]
	global_store_dwordx4 v[236:237], v[38:41], off offset:1024
	s_waitcnt vmcnt(8)
	v_pk_add_f32 v[184:185], v[136:137], 0 op_sel_hi:[1,0]
	v_pk_add_f32 v[186:187], v[138:139], 0 op_sel_hi:[1,0]
	s_waitcnt vmcnt(7)
	v_pk_add_f32 v[184:185], v[184:185], v[140:141]
	v_pk_add_f32 v[186:187], v[186:187], v[142:143]
	s_waitcnt vmcnt(6)
	v_pk_add_f32 v[184:185], v[184:185], v[144:145]
	v_pk_add_f32 v[186:187], v[186:187], v[146:147]
	s_waitcnt vmcnt(5)
	v_pk_add_f32 v[184:185], v[184:185], v[148:149]
	v_pk_add_f32 v[186:187], v[186:187], v[150:151]
	s_waitcnt vmcnt(4)
	v_pk_add_f32 v[184:185], v[184:185], v[152:153]
	v_pk_add_f32 v[186:187], v[186:187], v[154:155]
	s_waitcnt vmcnt(3)
	v_pk_add_f32 v[184:185], v[184:185], v[156:157]
	v_pk_add_f32 v[186:187], v[186:187], v[158:159]
	s_waitcnt vmcnt(2)
	v_pk_add_f32 v[184:185], v[184:185], v[164:165]
	v_pk_add_f32 v[186:187], v[186:187], v[166:167]
	s_waitcnt vmcnt(1)
	v_pk_add_f32 v[184:185], v[184:185], v[168:169]
	v_pk_add_f32 v[186:187], v[186:187], v[170:171]
	s_nop 0
	v_pk_fma_f32 v[58:59], v[66:67], v[184:185], v[58:59]
	v_pk_fma_f32 v[60:61], v[68:69], v[186:187], v[60:61]
	global_store_dwordx4 v[238:239], v[58:61], off offset:1024
	global_load_dwordx4 v[66:69], v[84:85], off
	v_mov_b64_e32 v[240:241], v[224:225]
	global_load_dwordx4 v[104:107], v[240:241], off offset:2048
	v_lshl_add_u64 v[240:241], v[240:241], 0, s[14:15]
	global_load_dwordx4 v[108:111], v[240:241], off offset:2048
	v_lshl_add_u64 v[240:241], v[240:241], 0, s[14:15]
	global_load_dwordx4 v[112:115], v[240:241], off offset:2048
	v_lshl_add_u64 v[240:241], v[240:241], 0, s[14:15]
	global_load_dwordx4 v[116:119], v[240:241], off offset:2048
	v_lshl_add_u64 v[240:241], v[240:241], 0, s[14:15]
	global_load_dwordx4 v[120:123], v[240:241], off offset:2048
	v_lshl_add_u64 v[240:241], v[240:241], 0, s[14:15]
	global_load_dwordx4 v[124:127], v[240:241], off offset:2048
	v_lshl_add_u64 v[240:241], v[240:241], 0, s[14:15]
	global_load_dwordx4 v[128:131], v[240:241], off offset:2048
	v_lshl_add_u64 v[240:241], v[240:241], 0, s[14:15]
	global_load_dwordx4 v[132:135], v[240:241], off offset:2048
	v_mov_b64_e32 v[240:241], v[226:227]
	global_load_dwordx4 v[136:139], v[240:241], off offset:2048
	v_lshl_add_u64 v[240:241], v[240:241], 0, s[14:15]
	global_load_dwordx4 v[140:143], v[240:241], off offset:2048
	v_lshl_add_u64 v[240:241], v[240:241], 0, s[14:15]
	global_load_dwordx4 v[144:147], v[240:241], off offset:2048
	v_lshl_add_u64 v[240:241], v[240:241], 0, s[14:15]
	global_load_dwordx4 v[148:151], v[240:241], off offset:2048
	v_lshl_add_u64 v[240:241], v[240:241], 0, s[14:15]
	global_load_dwordx4 v[152:155], v[240:241], off offset:2048
	v_lshl_add_u64 v[240:241], v[240:241], 0, s[14:15]
	global_load_dwordx4 v[156:159], v[240:241], off offset:2048
	v_lshl_add_u64 v[240:241], v[240:241], 0, s[14:15]
	global_load_dwordx4 v[164:167], v[240:241], off offset:2048
	v_lshl_add_u64 v[240:241], v[240:241], 0, s[14:15]
	global_load_dwordx4 v[168:171], v[240:241], off offset:2048
	s_waitcnt vmcnt(15)
	v_pk_add_f32 v[172:173], v[104:105], 0 op_sel_hi:[1,0]
	v_pk_add_f32 v[174:175], v[106:107], 0 op_sel_hi:[1,0]
	s_waitcnt vmcnt(14)
	v_pk_add_f32 v[172:173], v[172:173], v[108:109]
	v_pk_add_f32 v[174:175], v[174:175], v[110:111]
	s_waitcnt vmcnt(13)
	v_pk_add_f32 v[172:173], v[172:173], v[112:113]
	v_pk_add_f32 v[174:175], v[174:175], v[114:115]
	s_waitcnt vmcnt(12)
	v_pk_add_f32 v[172:173], v[172:173], v[116:117]
	v_pk_add_f32 v[174:175], v[174:175], v[118:119]
	s_waitcnt vmcnt(11)
	v_pk_add_f32 v[172:173], v[172:173], v[120:121]
	v_pk_add_f32 v[174:175], v[174:175], v[122:123]
	s_waitcnt vmcnt(10)
	v_pk_add_f32 v[172:173], v[172:173], v[124:125]
	v_pk_add_f32 v[174:175], v[174:175], v[126:127]
	s_waitcnt vmcnt(9)
	v_pk_add_f32 v[172:173], v[172:173], v[128:129]
	v_pk_add_f32 v[174:175], v[174:175], v[130:131]
	s_waitcnt vmcnt(8)
	v_pk_add_f32 v[172:173], v[172:173], v[132:133]
	v_pk_add_f32 v[174:175], v[174:175], v[134:135]
	s_nop 0
	v_pk_fma_f32 v[6:7], v[66:67], v[172:173], v[6:7]
	v_pk_fma_f32 v[8:9], v[68:69], v[174:175], v[8:9]
	global_store_dwordx4 v[232:233], v[6:9], off offset:2048
	s_waitcnt vmcnt(8)
	v_pk_add_f32 v[184:185], v[136:137], 0 op_sel_hi:[1,0]
	v_pk_add_f32 v[186:187], v[138:139], 0 op_sel_hi:[1,0]
	s_waitcnt vmcnt(7)
	v_pk_add_f32 v[184:185], v[184:185], v[140:141]
	v_pk_add_f32 v[186:187], v[186:187], v[142:143]
	s_waitcnt vmcnt(6)
	v_pk_add_f32 v[184:185], v[184:185], v[144:145]
	v_pk_add_f32 v[186:187], v[186:187], v[146:147]
	s_waitcnt vmcnt(5)
	v_pk_add_f32 v[184:185], v[184:185], v[148:149]
	v_pk_add_f32 v[186:187], v[186:187], v[150:151]
	s_waitcnt vmcnt(4)
	v_pk_add_f32 v[184:185], v[184:185], v[152:153]
	v_pk_add_f32 v[186:187], v[186:187], v[154:155]
	s_waitcnt vmcnt(3)
	v_pk_add_f32 v[184:185], v[184:185], v[156:157]
	v_pk_add_f32 v[186:187], v[186:187], v[158:159]
	s_waitcnt vmcnt(2)
	v_pk_add_f32 v[184:185], v[184:185], v[164:165]
	v_pk_add_f32 v[186:187], v[186:187], v[166:167]
	s_waitcnt vmcnt(1)
	v_pk_add_f32 v[184:185], v[184:185], v[168:169]
	v_pk_add_f32 v[186:187], v[186:187], v[170:171]
	s_nop 0
	v_pk_fma_f32 v[18:19], v[66:67], v[184:185], v[18:19]
	v_pk_fma_f32 v[20:21], v[68:69], v[186:187], v[20:21]
	global_store_dwordx4 v[234:235], v[18:21], off offset:2048
	v_mov_b64_e32 v[240:241], v[228:229]
	global_load_dwordx4 v[104:107], v[240:241], off offset:2048
	v_lshl_add_u64 v[240:241], v[240:241], 0, s[14:15]
	global_load_dwordx4 v[108:111], v[240:241], off offset:2048
	v_lshl_add_u64 v[240:241], v[240:241], 0, s[14:15]
	global_load_dwordx4 v[112:115], v[240:241], off offset:2048
	v_lshl_add_u64 v[240:241], v[240:241], 0, s[14:15]
	global_load_dwordx4 v[116:119], v[240:241], off offset:2048
	v_lshl_add_u64 v[240:241], v[240:241], 0, s[14:15]
	global_load_dwordx4 v[120:123], v[240:241], off offset:2048
	v_lshl_add_u64 v[240:241], v[240:241], 0, s[14:15]
	global_load_dwordx4 v[124:127], v[240:241], off offset:2048
	v_lshl_add_u64 v[240:241], v[240:241], 0, s[14:15]
	global_load_dwordx4 v[128:131], v[240:241], off offset:2048
	v_lshl_add_u64 v[240:241], v[240:241], 0, s[14:15]
	global_load_dwordx4 v[132:135], v[240:241], off offset:2048
	v_mov_b64_e32 v[240:241], v[230:231]
	global_load_dwordx4 v[136:139], v[240:241], off offset:2048
	v_lshl_add_u64 v[240:241], v[240:241], 0, s[14:15]
	global_load_dwordx4 v[140:143], v[240:241], off offset:2048
	v_lshl_add_u64 v[240:241], v[240:241], 0, s[14:15]
	global_load_dwordx4 v[144:147], v[240:241], off offset:2048
	v_lshl_add_u64 v[240:241], v[240:241], 0, s[14:15]
	global_load_dwordx4 v[148:151], v[240:241], off offset:2048
	v_lshl_add_u64 v[240:241], v[240:241], 0, s[14:15]
	global_load_dwordx4 v[152:155], v[240:241], off offset:2048
	v_lshl_add_u64 v[240:241], v[240:241], 0, s[14:15]
	global_load_dwordx4 v[156:159], v[240:241], off offset:2048
	v_lshl_add_u64 v[240:241], v[240:241], 0, s[14:15]
	global_load_dwordx4 v[164:167], v[240:241], off offset:2048
	v_lshl_add_u64 v[240:241], v[240:241], 0, s[14:15]
	global_load_dwordx4 v[168:171], v[240:241], off offset:2048
	s_waitcnt vmcnt(15)
	v_pk_add_f32 v[172:173], v[104:105], 0 op_sel_hi:[1,0]
	v_pk_add_f32 v[174:175], v[106:107], 0 op_sel_hi:[1,0]
	s_waitcnt vmcnt(14)
	v_pk_add_f32 v[172:173], v[172:173], v[108:109]
	v_pk_add_f32 v[174:175], v[174:175], v[110:111]
	s_waitcnt vmcnt(13)
	v_pk_add_f32 v[172:173], v[172:173], v[112:113]
	v_pk_add_f32 v[174:175], v[174:175], v[114:115]
	s_waitcnt vmcnt(12)
	v_pk_add_f32 v[172:173], v[172:173], v[116:117]
	v_pk_add_f32 v[174:175], v[174:175], v[118:119]
	s_waitcnt vmcnt(11)
	v_pk_add_f32 v[172:173], v[172:173], v[120:121]
	v_pk_add_f32 v[174:175], v[174:175], v[122:123]
	s_waitcnt vmcnt(10)
	v_pk_add_f32 v[172:173], v[172:173], v[124:125]
	v_pk_add_f32 v[174:175], v[174:175], v[126:127]
	s_waitcnt vmcnt(9)
	v_pk_add_f32 v[172:173], v[172:173], v[128:129]
	v_pk_add_f32 v[174:175], v[174:175], v[130:131]
	s_waitcnt vmcnt(8)
	v_pk_add_f32 v[172:173], v[172:173], v[132:133]
	v_pk_add_f32 v[174:175], v[174:175], v[134:135]
	s_nop 0
	v_pk_fma_f32 v[30:31], v[66:67], v[172:173], v[30:31]
	v_pk_fma_f32 v[32:33], v[68:69], v[174:175], v[32:33]
	global_store_dwordx4 v[236:237], v[30:33], off offset:2048
	s_waitcnt vmcnt(8)
	v_pk_add_f32 v[184:185], v[136:137], 0 op_sel_hi:[1,0]
	v_pk_add_f32 v[186:187], v[138:139], 0 op_sel_hi:[1,0]
	s_waitcnt vmcnt(7)
	v_pk_add_f32 v[184:185], v[184:185], v[140:141]
	v_pk_add_f32 v[186:187], v[186:187], v[142:143]
	s_waitcnt vmcnt(6)
	v_pk_add_f32 v[184:185], v[184:185], v[144:145]
	v_pk_add_f32 v[186:187], v[186:187], v[146:147]
	s_waitcnt vmcnt(5)
	v_pk_add_f32 v[184:185], v[184:185], v[148:149]
	v_pk_add_f32 v[186:187], v[186:187], v[150:151]
	s_waitcnt vmcnt(4)
	v_pk_add_f32 v[184:185], v[184:185], v[152:153]
	v_pk_add_f32 v[186:187], v[186:187], v[154:155]
	s_waitcnt vmcnt(3)
	v_pk_add_f32 v[184:185], v[184:185], v[156:157]
	v_pk_add_f32 v[186:187], v[186:187], v[158:159]
	s_waitcnt vmcnt(2)
	v_pk_add_f32 v[184:185], v[184:185], v[164:165]
	v_pk_add_f32 v[186:187], v[186:187], v[166:167]
	s_waitcnt vmcnt(1)
	v_pk_add_f32 v[184:185], v[184:185], v[168:169]
	v_pk_add_f32 v[186:187], v[186:187], v[170:171]
	s_nop 0
	v_pk_fma_f32 v[50:51], v[66:67], v[184:185], v[50:51]
	v_pk_fma_f32 v[52:53], v[68:69], v[186:187], v[52:53]
	global_store_dwordx4 v[238:239], v[50:53], off offset:2048
	global_load_dwordx4 v[66:69], v[86:87], off
	v_mov_b64_e32 v[240:241], v[224:225]
	global_load_dwordx4 v[104:107], v[240:241], off offset:3072
	v_lshl_add_u64 v[240:241], v[240:241], 0, s[14:15]
	global_load_dwordx4 v[108:111], v[240:241], off offset:3072
	v_lshl_add_u64 v[240:241], v[240:241], 0, s[14:15]
	global_load_dwordx4 v[112:115], v[240:241], off offset:3072
	v_lshl_add_u64 v[240:241], v[240:241], 0, s[14:15]
	global_load_dwordx4 v[116:119], v[240:241], off offset:3072
	v_lshl_add_u64 v[240:241], v[240:241], 0, s[14:15]
	global_load_dwordx4 v[120:123], v[240:241], off offset:3072
	v_lshl_add_u64 v[240:241], v[240:241], 0, s[14:15]
	global_load_dwordx4 v[124:127], v[240:241], off offset:3072
	v_lshl_add_u64 v[240:241], v[240:241], 0, s[14:15]
	global_load_dwordx4 v[128:131], v[240:241], off offset:3072
	v_lshl_add_u64 v[240:241], v[240:241], 0, s[14:15]
	global_load_dwordx4 v[132:135], v[240:241], off offset:3072
	v_mov_b64_e32 v[240:241], v[226:227]
	global_load_dwordx4 v[136:139], v[240:241], off offset:3072
	v_lshl_add_u64 v[240:241], v[240:241], 0, s[14:15]
	global_load_dwordx4 v[140:143], v[240:241], off offset:3072
	v_lshl_add_u64 v[240:241], v[240:241], 0, s[14:15]
	global_load_dwordx4 v[144:147], v[240:241], off offset:3072
	v_lshl_add_u64 v[240:241], v[240:241], 0, s[14:15]
	global_load_dwordx4 v[148:151], v[240:241], off offset:3072
	v_lshl_add_u64 v[240:241], v[240:241], 0, s[14:15]
	global_load_dwordx4 v[152:155], v[240:241], off offset:3072
	v_lshl_add_u64 v[240:241], v[240:241], 0, s[14:15]
	global_load_dwordx4 v[156:159], v[240:241], off offset:3072
	v_lshl_add_u64 v[240:241], v[240:241], 0, s[14:15]
	global_load_dwordx4 v[164:167], v[240:241], off offset:3072
	v_lshl_add_u64 v[240:241], v[240:241], 0, s[14:15]
	global_load_dwordx4 v[168:171], v[240:241], off offset:3072
	s_waitcnt vmcnt(15)
	v_pk_add_f32 v[172:173], v[104:105], 0 op_sel_hi:[1,0]
	v_pk_add_f32 v[174:175], v[106:107], 0 op_sel_hi:[1,0]
	s_waitcnt vmcnt(14)
	v_pk_add_f32 v[172:173], v[172:173], v[108:109]
	v_pk_add_f32 v[174:175], v[174:175], v[110:111]
	s_waitcnt vmcnt(13)
	v_pk_add_f32 v[172:173], v[172:173], v[112:113]
	v_pk_add_f32 v[174:175], v[174:175], v[114:115]
	s_waitcnt vmcnt(12)
	v_pk_add_f32 v[172:173], v[172:173], v[116:117]
	v_pk_add_f32 v[174:175], v[174:175], v[118:119]
	s_waitcnt vmcnt(11)
	v_pk_add_f32 v[172:173], v[172:173], v[120:121]
	v_pk_add_f32 v[174:175], v[174:175], v[122:123]
	s_waitcnt vmcnt(10)
	v_pk_add_f32 v[172:173], v[172:173], v[124:125]
	v_pk_add_f32 v[174:175], v[174:175], v[126:127]
	s_waitcnt vmcnt(9)
	v_pk_add_f32 v[172:173], v[172:173], v[128:129]
	v_pk_add_f32 v[174:175], v[174:175], v[130:131]
	s_waitcnt vmcnt(8)
	v_pk_add_f32 v[172:173], v[172:173], v[132:133]
	v_pk_add_f32 v[174:175], v[174:175], v[134:135]
	s_nop 0
	v_pk_fma_f32 v[2:3], v[66:67], v[172:173], v[2:3]
	v_pk_fma_f32 v[4:5], v[68:69], v[174:175], v[4:5]
	global_store_dwordx4 v[232:233], v[2:5], off offset:3072
	s_waitcnt vmcnt(8)
	v_pk_add_f32 v[184:185], v[136:137], 0 op_sel_hi:[1,0]
	v_pk_add_f32 v[186:187], v[138:139], 0 op_sel_hi:[1,0]
	s_waitcnt vmcnt(7)
	v_pk_add_f32 v[184:185], v[184:185], v[140:141]
	v_pk_add_f32 v[186:187], v[186:187], v[142:143]
	s_waitcnt vmcnt(6)
	v_pk_add_f32 v[184:185], v[184:185], v[144:145]
	v_pk_add_f32 v[186:187], v[186:187], v[146:147]
	s_waitcnt vmcnt(5)
	v_pk_add_f32 v[184:185], v[184:185], v[148:149]
	v_pk_add_f32 v[186:187], v[186:187], v[150:151]
	s_waitcnt vmcnt(4)
	v_pk_add_f32 v[184:185], v[184:185], v[152:153]
	v_pk_add_f32 v[186:187], v[186:187], v[154:155]
	s_waitcnt vmcnt(3)
	v_pk_add_f32 v[184:185], v[184:185], v[156:157]
	v_pk_add_f32 v[186:187], v[186:187], v[158:159]
	s_waitcnt vmcnt(2)
	v_pk_add_f32 v[184:185], v[184:185], v[164:165]
	v_pk_add_f32 v[186:187], v[186:187], v[166:167]
	s_waitcnt vmcnt(1)
	v_pk_add_f32 v[184:185], v[184:185], v[168:169]
	v_pk_add_f32 v[186:187], v[186:187], v[170:171]
	s_nop 0
	v_pk_fma_f32 v[10:11], v[66:67], v[184:185], v[10:11]
	v_pk_fma_f32 v[12:13], v[68:69], v[186:187], v[12:13]
	global_store_dwordx4 v[234:235], v[10:13], off offset:3072
	v_mov_b64_e32 v[240:241], v[228:229]
	global_load_dwordx4 v[104:107], v[240:241], off offset:3072
	v_lshl_add_u64 v[240:241], v[240:241], 0, s[14:15]
	global_load_dwordx4 v[108:111], v[240:241], off offset:3072
	v_lshl_add_u64 v[240:241], v[240:241], 0, s[14:15]
	global_load_dwordx4 v[112:115], v[240:241], off offset:3072
	v_lshl_add_u64 v[240:241], v[240:241], 0, s[14:15]
	global_load_dwordx4 v[116:119], v[240:241], off offset:3072
	v_lshl_add_u64 v[240:241], v[240:241], 0, s[14:15]
	global_load_dwordx4 v[120:123], v[240:241], off offset:3072
	v_lshl_add_u64 v[240:241], v[240:241], 0, s[14:15]
	global_load_dwordx4 v[124:127], v[240:241], off offset:3072
	v_lshl_add_u64 v[240:241], v[240:241], 0, s[14:15]
	global_load_dwordx4 v[128:131], v[240:241], off offset:3072
	v_lshl_add_u64 v[240:241], v[240:241], 0, s[14:15]
	global_load_dwordx4 v[132:135], v[240:241], off offset:3072
	v_mov_b64_e32 v[240:241], v[230:231]
	global_load_dwordx4 v[136:139], v[240:241], off offset:3072
	v_lshl_add_u64 v[240:241], v[240:241], 0, s[14:15]
	global_load_dwordx4 v[140:143], v[240:241], off offset:3072
	v_lshl_add_u64 v[240:241], v[240:241], 0, s[14:15]
	global_load_dwordx4 v[144:147], v[240:241], off offset:3072
	v_lshl_add_u64 v[240:241], v[240:241], 0, s[14:15]
	global_load_dwordx4 v[148:151], v[240:241], off offset:3072
	v_lshl_add_u64 v[240:241], v[240:241], 0, s[14:15]
	global_load_dwordx4 v[152:155], v[240:241], off offset:3072
	v_lshl_add_u64 v[240:241], v[240:241], 0, s[14:15]
	global_load_dwordx4 v[156:159], v[240:241], off offset:3072
	v_lshl_add_u64 v[240:241], v[240:241], 0, s[14:15]
	global_load_dwordx4 v[164:167], v[240:241], off offset:3072
	v_lshl_add_u64 v[240:241], v[240:241], 0, s[14:15]
	global_load_dwordx4 v[168:171], v[240:241], off offset:3072
	s_waitcnt vmcnt(15)
	v_pk_add_f32 v[172:173], v[104:105], 0 op_sel_hi:[1,0]
	v_pk_add_f32 v[174:175], v[106:107], 0 op_sel_hi:[1,0]
	s_waitcnt vmcnt(14)
	v_pk_add_f32 v[172:173], v[172:173], v[108:109]
	v_pk_add_f32 v[174:175], v[174:175], v[110:111]
	s_waitcnt vmcnt(13)
	v_pk_add_f32 v[172:173], v[172:173], v[112:113]
	v_pk_add_f32 v[174:175], v[174:175], v[114:115]
	s_waitcnt vmcnt(12)
	v_pk_add_f32 v[172:173], v[172:173], v[116:117]
	v_pk_add_f32 v[174:175], v[174:175], v[118:119]
	s_waitcnt vmcnt(11)
	v_pk_add_f32 v[172:173], v[172:173], v[120:121]
	v_pk_add_f32 v[174:175], v[174:175], v[122:123]
	s_waitcnt vmcnt(10)
	v_pk_add_f32 v[172:173], v[172:173], v[124:125]
	v_pk_add_f32 v[174:175], v[174:175], v[126:127]
	s_waitcnt vmcnt(9)
	v_pk_add_f32 v[172:173], v[172:173], v[128:129]
	v_pk_add_f32 v[174:175], v[174:175], v[130:131]
	s_waitcnt vmcnt(8)
	v_pk_add_f32 v[172:173], v[172:173], v[132:133]
	v_pk_add_f32 v[174:175], v[174:175], v[134:135]
	s_nop 0
	v_pk_fma_f32 v[22:23], v[66:67], v[172:173], v[22:23]
	v_pk_fma_f32 v[24:25], v[68:69], v[174:175], v[24:25]
	global_store_dwordx4 v[236:237], v[22:25], off offset:3072
	s_waitcnt vmcnt(8)
	v_pk_add_f32 v[184:185], v[136:137], 0 op_sel_hi:[1,0]
	v_pk_add_f32 v[186:187], v[138:139], 0 op_sel_hi:[1,0]
	s_waitcnt vmcnt(7)
	v_pk_add_f32 v[184:185], v[184:185], v[140:141]
	v_pk_add_f32 v[186:187], v[186:187], v[142:143]
	s_waitcnt vmcnt(6)
	v_pk_add_f32 v[184:185], v[184:185], v[144:145]
	v_pk_add_f32 v[186:187], v[186:187], v[146:147]
	s_waitcnt vmcnt(5)
	v_pk_add_f32 v[184:185], v[184:185], v[148:149]
	v_pk_add_f32 v[186:187], v[186:187], v[150:151]
	s_waitcnt vmcnt(4)
	v_pk_add_f32 v[184:185], v[184:185], v[152:153]
	v_pk_add_f32 v[186:187], v[186:187], v[154:155]
	s_waitcnt vmcnt(3)
	v_pk_add_f32 v[184:185], v[184:185], v[156:157]
	v_pk_add_f32 v[186:187], v[186:187], v[158:159]
	s_waitcnt vmcnt(2)
	v_pk_add_f32 v[184:185], v[184:185], v[164:165]
	v_pk_add_f32 v[186:187], v[186:187], v[166:167]
	s_waitcnt vmcnt(1)
	v_pk_add_f32 v[184:185], v[184:185], v[168:169]
	v_pk_add_f32 v[186:187], v[186:187], v[170:171]
	s_nop 0
	v_pk_fma_f32 v[42:43], v[66:67], v[184:185], v[42:43]
	v_pk_fma_f32 v[44:45], v[68:69], v[186:187], v[44:45]
	global_store_dwordx4 v[238:239], v[42:45], off offset:3072
	s_branch .LBB0_1287
